# GEMM accumulators zeroed with 64 v_mov_b64 (literal 0) instead of 128 v_mov_b32 per unit
# speedup vs baseline: 1.0183x; 1.0055x over previous
; template <class Epi, class Sched, bool ALIGN_EPI = false, bool SP2 = false>
; __device__ __forceinline__ void gemm_phase(PG8_LAS unsigned char* lds, const Sched& S, const Epi& E, int wave_id) {
;     ...
; #pragma unroll
;         for (int a = 0; a < 2; ++a)
; #pragma unroll
;             for (int b = 0; b < 2; ++b)
; #pragma unroll
;                 for (int m = 0; m < 4; ++m)
; #pragma unroll
;                     for (int n = 0; n < 2; ++n) acc[a][b][m][n] = (f32x4){0.f, 0.f, 0.f, 0.f};
;         cur = nxt; cA = nA; cB = nB; ++ui;
.LBB0_88:
	s_add_u32 s38, s44, 0x80080
	s_addc_u32 s39, s45, 0
	s_add_u32 s16, s42, 0x100
	v_mov_b64_e32 v[2:3], 0
	v_mov_b64_e32 v[4:5], 0
	v_mov_b64_e32 v[6:7], 0
	v_mov_b64_e32 v[8:9], 0
	v_mov_b64_e32 v[10:11], 0
	v_mov_b64_e32 v[12:13], 0
	v_mov_b64_e32 v[14:15], 0
	v_mov_b64_e32 v[16:17], 0
	v_mov_b64_e32 v[18:19], 0
	v_mov_b64_e32 v[20:21], 0
	v_mov_b64_e32 v[22:23], 0
	v_mov_b64_e32 v[24:25], 0
	v_mov_b64_e32 v[26:27], 0
	v_mov_b64_e32 v[28:29], 0
	v_mov_b64_e32 v[30:31], 0
	v_mov_b64_e32 v[32:33], 0
	v_mov_b64_e32 v[42:43], 0
	v_mov_b64_e32 v[44:45], 0
	v_mov_b64_e32 v[46:47], 0
	v_mov_b64_e32 v[48:49], 0
	v_mov_b64_e32 v[58:59], 0
	v_mov_b64_e32 v[60:61], 0
	v_mov_b64_e32 v[62:63], 0
	v_mov_b64_e32 v[64:65], 0
	v_mov_b64_e32 v[66:67], 0
	v_mov_b64_e32 v[68:69], 0
	v_mov_b64_e32 v[70:71], 0
	v_mov_b64_e32 v[72:73], 0
	v_mov_b64_e32 v[74:75], 0
	v_mov_b64_e32 v[76:77], 0
	v_mov_b64_e32 v[78:79], 0
	v_mov_b64_e32 v[80:81], 0
	v_mov_b64_e32 v[82:83], 0
	v_mov_b64_e32 v[84:85], 0
	v_mov_b64_e32 v[86:87], 0
	v_mov_b64_e32 v[88:89], 0
	v_mov_b64_e32 v[90:91], 0
	v_mov_b64_e32 v[92:93], 0
	v_mov_b64_e32 v[94:95], 0
	v_mov_b64_e32 v[96:97], 0
	v_mov_b64_e32 v[98:99], 0
	v_mov_b64_e32 v[100:101], 0
	v_mov_b64_e32 v[102:103], 0
	v_mov_b64_e32 v[104:105], 0
	v_mov_b64_e32 v[106:107], 0
	v_mov_b64_e32 v[108:109], 0
	v_mov_b64_e32 v[110:111], 0
	v_mov_b64_e32 v[112:113], 0
	v_mov_b64_e32 v[114:115], 0
	v_mov_b64_e32 v[116:117], 0
	v_mov_b64_e32 v[118:119], 0
	v_mov_b64_e32 v[120:121], 0
	v_mov_b64_e32 v[122:123], 0
	v_mov_b64_e32 v[124:125], 0
	v_mov_b64_e32 v[126:127], 0
	v_mov_b64_e32 v[128:129], 0
	v_mov_b64_e32 v[130:131], 0
	v_mov_b64_e32 v[132:133], 0
	v_mov_b64_e32 v[134:135], 0
	v_mov_b64_e32 v[136:137], 0
	v_mov_b64_e32 v[138:139], 0
	v_mov_b64_e32 v[140:141], 0
	v_mov_b64_e32 v[142:143], 0
	v_mov_b64_e32 v[144:145], 0
	s_addc_u32 s17, s43, 0
	s_mov_b32 s19, -2

; template <class Epi, class Sched, bool ALIGN_EPI = false, bool SP2 = false>
; __device__ __forceinline__ void gemm_phase(PG8_LAS unsigned char* lds, const Sched& S, const Epi& E, int wave_id) {
;     ...
; #pragma unroll
;         for (int a = 0; a < 2; ++a)
; #pragma unroll
;             for (int b = 0; b < 2; ++b)
; #pragma unroll
;                 for (int m = 0; m < 4; ++m)
; #pragma unroll
;                     for (int n = 0; n < 2; ++n) acc[a][b][m][n] = (f32x4){0.f, 0.f, 0.f, 0.f};
;         cur = nxt; cA = nA; cB = nB; ++ui;
.LBB0_838:
	s_add_i32 s30, s50, -2
	s_add_u32 s38, s44, 0x80080
	s_addc_u32 s39, s45, 0
	s_add_u32 s46, s40, 0x100
	v_mov_b64_e32 v[2:3], 0
	v_mov_b64_e32 v[4:5], 0
	v_mov_b64_e32 v[6:7], 0
	v_mov_b64_e32 v[8:9], 0
	v_mov_b64_e32 v[10:11], 0
	v_mov_b64_e32 v[12:13], 0
	v_mov_b64_e32 v[14:15], 0
	v_mov_b64_e32 v[16:17], 0
	v_mov_b64_e32 v[18:19], 0
	v_mov_b64_e32 v[20:21], 0
	v_mov_b64_e32 v[22:23], 0
	v_mov_b64_e32 v[24:25], 0
	v_mov_b64_e32 v[26:27], 0
	v_mov_b64_e32 v[28:29], 0
	v_mov_b64_e32 v[30:31], 0
	v_mov_b64_e32 v[32:33], 0
	v_mov_b64_e32 v[34:35], 0
	v_mov_b64_e32 v[36:37], 0
	v_mov_b64_e32 v[38:39], 0
	v_mov_b64_e32 v[40:41], 0
	v_mov_b64_e32 v[42:43], 0
	v_mov_b64_e32 v[44:45], 0
	v_mov_b64_e32 v[46:47], 0
	v_mov_b64_e32 v[48:49], 0
	v_mov_b64_e32 v[50:51], 0
	v_mov_b64_e32 v[52:53], 0
	v_mov_b64_e32 v[54:55], 0
	v_mov_b64_e32 v[56:57], 0
	v_mov_b64_e32 v[58:59], 0
	v_mov_b64_e32 v[60:61], 0
	v_mov_b64_e32 v[62:63], 0
	v_mov_b64_e32 v[64:65], 0
	v_mov_b64_e32 v[66:67], 0
	v_mov_b64_e32 v[68:69], 0
	v_mov_b64_e32 v[70:71], 0
	v_mov_b64_e32 v[72:73], 0
	v_mov_b64_e32 v[74:75], 0
	v_mov_b64_e32 v[76:77], 0
	v_mov_b64_e32 v[78:79], 0
	v_mov_b64_e32 v[80:81], 0
	v_mov_b64_e32 v[82:83], 0
	v_mov_b64_e32 v[84:85], 0
	v_mov_b64_e32 v[86:87], 0
	v_mov_b64_e32 v[88:89], 0
	v_mov_b64_e32 v[90:91], 0
	v_mov_b64_e32 v[92:93], 0
	v_mov_b64_e32 v[94:95], 0
	v_mov_b64_e32 v[96:97], 0
	v_mov_b64_e32 v[98:99], 0
	v_mov_b64_e32 v[100:101], 0
	v_mov_b64_e32 v[102:103], 0
	v_mov_b64_e32 v[104:105], 0
	v_mov_b64_e32 v[106:107], 0
	v_mov_b64_e32 v[108:109], 0
	v_mov_b64_e32 v[110:111], 0
	v_mov_b64_e32 v[112:113], 0
	v_mov_b64_e32 v[114:115], 0
	v_mov_b64_e32 v[116:117], 0
	v_mov_b64_e32 v[118:119], 0
	v_mov_b64_e32 v[120:121], 0
	v_mov_b64_e32 v[122:123], 0
	v_mov_b64_e32 v[124:125], 0
	v_mov_b64_e32 v[126:127], 0
	v_mov_b64_e32 v[128:129], 0
	s_addc_u32 s47, s41, 0
	s_mov_b32 s40, 0

; template <class Epi, class Sched, bool ALIGN_EPI = false, bool SP2 = false>
; __device__ __forceinline__ void gemm_phase(PG8_LAS unsigned char* lds, const Sched& S, const Epi& E, int wave_id) {
;     ...
;         for (int a = 0; a < 2; ++a)
; #pragma unroll
;             for (int b = 0; b < 2; ++b)
; #pragma unroll
;                 for (int m = 0; m < 4; ++m)
; #pragma unroll
;                     for (int n = 0; n < 2; ++n) acc[a][b][m][n] = (f32x4){0.f, 0.f, 0.f, 0.f};
;         cur = nxt; cA = nA; cB = nB; ++ui;
.LBB0_1038:
	s_add_u32 s42, s42, 0x80080
	s_addc_u32 s43, s43, 0
	s_add_u32 s19, s44, 0x100
	v_mov_b64_e32 v[2:3], 0
	v_mov_b64_e32 v[4:5], 0
	v_mov_b64_e32 v[6:7], 0
	v_mov_b64_e32 v[8:9], 0
	v_mov_b64_e32 v[10:11], 0
	v_mov_b64_e32 v[12:13], 0
	v_mov_b64_e32 v[14:15], 0
	v_mov_b64_e32 v[16:17], 0
	v_mov_b64_e32 v[18:19], 0
	v_mov_b64_e32 v[20:21], 0
	v_mov_b64_e32 v[22:23], 0
	v_mov_b64_e32 v[24:25], 0
	v_mov_b64_e32 v[26:27], 0
	v_mov_b64_e32 v[28:29], 0
	v_mov_b64_e32 v[30:31], 0
	v_mov_b64_e32 v[32:33], 0
	v_mov_b64_e32 v[34:35], 0
	v_mov_b64_e32 v[36:37], 0
	v_mov_b64_e32 v[38:39], 0
	v_mov_b64_e32 v[40:41], 0
	v_mov_b64_e32 v[42:43], 0
	v_mov_b64_e32 v[44:45], 0
	v_mov_b64_e32 v[46:47], 0
	v_mov_b64_e32 v[48:49], 0
	v_mov_b64_e32 v[50:51], 0
	v_mov_b64_e32 v[52:53], 0
	v_mov_b64_e32 v[54:55], 0
	v_mov_b64_e32 v[56:57], 0
	v_mov_b64_e32 v[58:59], 0
	v_mov_b64_e32 v[60:61], 0
	v_mov_b64_e32 v[62:63], 0
	v_mov_b64_e32 v[64:65], 0
	v_mov_b64_e32 v[66:67], 0
	v_mov_b64_e32 v[68:69], 0
	v_mov_b64_e32 v[70:71], 0
	v_mov_b64_e32 v[72:73], 0
	v_mov_b64_e32 v[74:75], 0
	v_mov_b64_e32 v[76:77], 0
	v_mov_b64_e32 v[78:79], 0
	v_mov_b64_e32 v[80:81], 0
	v_mov_b64_e32 v[82:83], 0
	v_mov_b64_e32 v[84:85], 0
	v_mov_b64_e32 v[86:87], 0
	v_mov_b64_e32 v[88:89], 0
	v_mov_b64_e32 v[90:91], 0
	v_mov_b64_e32 v[92:93], 0
	v_mov_b64_e32 v[94:95], 0
	v_mov_b64_e32 v[96:97], 0
	v_mov_b64_e32 v[98:99], 0
	v_mov_b64_e32 v[100:101], 0
	v_mov_b64_e32 v[102:103], 0
	v_mov_b64_e32 v[104:105], 0
	v_mov_b64_e32 v[106:107], 0
	v_mov_b64_e32 v[108:109], 0
	v_mov_b64_e32 v[110:111], 0
	v_mov_b64_e32 v[112:113], 0
	v_mov_b64_e32 v[114:115], 0
	v_mov_b64_e32 v[116:117], 0
	v_mov_b64_e32 v[118:119], 0
	v_mov_b64_e32 v[120:121], 0
	v_mov_b64_e32 v[122:123], 0
	v_mov_b64_e32 v[124:125], 0
	v_mov_b64_e32 v[126:127], 0
	v_mov_b64_e32 v[128:129], 0
	s_addc_u32 s50, s45, 0
	s_mov_b32 s51, -2
